# NA: bias table loads batched; query rows remapped so each XCD works on consecutive rows of one batch (L2 reuse of K/V windows)
# speedup vs baseline: 1.0355x; 1.0355x over previous
.LBB0_691:
	v_readlane_b32 s0, v254, 19
	s_abs_i32 s2, s0
	v_cvt_f32_u32_e32 v0, s2
	s_sub_i32 s21, 0, s2
	s_mov_b32 s20, s0
	s_add_i32 s3, s20, 0x7ff
	v_rcp_iflag_f32_e32 v0, v0
	s_xor_b32 s20, s3, s20
	s_abs_i32 s3, s3
	s_ashr_i32 s20, s20, 31
	v_mul_f32_e32 v0, 0x4f7ffffe, v0
	v_cvt_u32_f32_e32 v0, v0
	v_readlane_b32 s1, v254, 20
	v_readlane_b32 s68, v254, 16
	s_mov_b64 s[0:1], 0
	v_readfirstlane_b32 s22, v0
	s_mul_i32 s21, s21, s22
	s_mul_hi_u32 s21, s22, s21
	s_add_i32 s22, s22, s21
	s_mul_hi_u32 s21, s3, s22
	s_mul_i32 s22, s21, s2
	s_sub_i32 s3, s3, s22
	s_add_i32 s22, s21, 1
	s_sub_i32 s23, s3, s2
	s_cmp_ge_u32 s3, s2
	s_cselect_b32 s21, s22, s21
	s_cselect_b32 s3, s23, s3
	s_add_i32 s22, s21, 1
	s_cmp_ge_u32 s3, s2
	s_cselect_b32 s2, s22, s21
	s_xor_b32 s2, s2, s20
	s_waitcnt lgkmcnt(0)
	v_mov_b32_e32 v1, v181
	s_sub_i32 s20, s2, s20
	s_mov_b32 s21, s68
	s_mul_i32 s34, s21, s20
	s_add_i32 s2, s34, s20
	s_min_i32 s2, s2, 0x800
	v_writelane_b32 v254, s2, 59
	s_cmp_ge_i32 s34, s2
	v_readfirstlane_b32 s22, v1
	s_cbranch_scc1 .LBB0_1802
	s_mov_b32 s40, 0
	v_writelane_b32 v255, s40, 11
	v_writelane_b32 v255, s40, 12
	v_readlane_b32 s40, v254, 19
	s_cmp_lg_u32 s40, 0x100
	s_cbranch_scc1 .Lna_map_done
	s_cmp_lg_u32 s20, 8
	s_cbranch_scc1 .Lna_map_done
	s_mov_b32 s40, 1
	v_writelane_b32 v255, s40, 12
	s_and_b32 s40, s21, 7
	s_lshl_b32 s40, s40, 8
	s_lshr_b32 s34, s21, 3
	s_or_b32 s34, s34, s40
	v_writelane_b32 v255, s34, 10
	s_movk_i32 s40, 0x800
	v_writelane_b32 v254, s40, 59
.Lna_map_done:
	v_readlane_b32 s40, v254, 0
	v_readlane_b32 s50, v254, 10
	v_readlane_b32 s51, v254, 11
	s_add_u32 s2, s50, s0
	s_addc_u32 s3, s51, s1
	v_readlane_b32 s0, v254, 39
	v_readlane_b32 s1, v254, 40
	s_mulk_i32 s0, 0x744
	s_ashr_i32 s1, s0, 31
	s_lshl_b64 s[0:1], s[0:1], 2
	s_add_u32 s2, s2, s0
	s_addc_u32 s3, s3, s1
	s_ashr_i32 s0, s22, 6
	s_and_b32 s26, s0, 3
	v_and_b32_e32 v3, 15, v1
	s_mulk_i32 s0, 0x4c00
	v_sub_u32_e64 v0, s26, 1 clamp
	v_lshl_or_b32 v205, s26, 4, v3
	s_add_i32 s40, s0, 0
	v_cmp_gt_u32_e64 s[0:1], 2, v0
	v_bfe_u32 v2, v1, 4, 2
	v_sub_u32_e64 v0, v205, 8 clamp
	v_min_u32_e32 v4, 48, v0
	v_lshlrev_b32_e32 v0, 2, v2
	v_or_b32_e32 v7, 1, v0
	v_sub_u32_e32 v8, v7, v205
	v_readlane_b32 s41, v254, 1
	v_readlane_b32 s42, v254, 2
	v_readlane_b32 s43, v254, 3
	v_readlane_b32 s44, v254, 4
	v_readlane_b32 s45, v254, 5
	v_readlane_b32 s46, v254, 6
	v_readlane_b32 s47, v254, 7
	v_readlane_b32 s48, v254, 8
	v_readlane_b32 s49, v254, 9
	v_readlane_b32 s52, v254, 12
	v_readlane_b32 s53, v254, 13
	v_readlane_b32 s54, v254, 14
	v_readlane_b32 s55, v254, 15
	v_writelane_b32 v254, s0, 27
	v_max_i32_e32 v8, -15, v8
	v_add_u32_e32 v8, 15, v8
	v_writelane_b32 v254, s1, 28
	v_cmp_ge_u32_e64 s[0:1], v7, v4
	v_sub_u32_e32 v6, v0, v205
	v_max_i32_e32 v6, -15, v6
	v_cndmask_b32_e64 v7, -1, v8, s[0:1]
	v_or_b32_e32 v8, 2, v0
	v_sub_u32_e32 v9, v8, v205
	v_max_i32_e32 v9, -15, v9
	v_add_u32_e32 v9, 15, v9
	v_cmp_ge_u32_e64 s[0:1], v8, v4
	v_add_u32_e32 v6, 15, v6
	v_cmp_lt_u32_e32 vcc, v0, v4
	v_cndmask_b32_e64 v8, -1, v9, s[0:1]
	v_or_b32_e32 v9, 3, v0
	v_sub_u32_e32 v10, v9, v205
	v_max_i32_e32 v10, -15, v10
	v_add_u32_e32 v10, 15, v10
	v_cmp_ge_u32_e64 s[0:1], v9, v4
	v_add_u32_e32 v5, 16, v4
	v_cndmask_b32_e64 v6, v6, -1, vcc
	v_cndmask_b32_e64 v9, -1, v10, s[0:1]
	v_or_b32_e32 v10, 16, v0
	v_cmp_ge_u32_e64 s[0:1], v10, v4
	v_sub_u32_e32 v10, v10, v205
	v_med3_i32 v10, v10, -15, 15
	v_add_u32_e32 v10, 15, v10
	s_and_b64 vcc, s[0:1], vcc
	v_or_b32_e32 v11, 17, v0
	v_cndmask_b32_e32 v10, -1, v10, vcc
	v_cmp_ge_u32_e32 vcc, v11, v4
	v_cmp_lt_u32_e64 s[0:1], v11, v5
	v_sub_u32_e32 v11, v11, v205
	v_med3_i32 v11, v11, -15, 15
	v_add_u32_e32 v11, 15, v11
	s_and_b64 vcc, vcc, s[0:1]
	v_or_b32_e32 v12, 18, v0
	v_cndmask_b32_e32 v11, -1, v11, vcc
	v_cmp_ge_u32_e32 vcc, v12, v4
	v_cmp_lt_u32_e64 s[0:1], v12, v5
	v_sub_u32_e32 v12, v12, v205
	v_med3_i32 v12, v12, -15, 15
	v_add_u32_e32 v12, 15, v12
	s_and_b64 vcc, vcc, s[0:1]
	v_or_b32_e32 v13, 19, v0
	v_cndmask_b32_e32 v12, -1, v12, vcc
	v_cmp_ge_u32_e32 vcc, v13, v4
	v_cmp_lt_u32_e64 s[0:1], v13, v5
	v_sub_u32_e32 v13, v13, v205
	v_med3_i32 v13, v13, -15, 15
	v_add_u32_e32 v13, 15, v13
	s_and_b64 vcc, vcc, s[0:1]
	v_or_b32_e32 v14, 32, v0
	v_cndmask_b32_e32 v13, -1, v13, vcc
	v_cmp_ge_u32_e32 vcc, v14, v4
	v_cmp_lt_u32_e64 s[0:1], v14, v5
	v_sub_u32_e32 v14, v14, v205
	v_med3_i32 v14, v14, -15, 15
	v_add_u32_e32 v14, 15, v14
	s_and_b64 vcc, vcc, s[0:1]
	v_or_b32_e32 v15, 33, v0
	v_cndmask_b32_e32 v14, -1, v14, vcc
	v_cmp_ge_u32_e32 vcc, v15, v4
	v_cmp_lt_u32_e64 s[0:1], v15, v5
	v_sub_u32_e32 v15, v15, v205
	v_med3_i32 v15, v15, -15, 15
	v_add_u32_e32 v15, 15, v15
	s_and_b64 vcc, vcc, s[0:1]
	v_or_b32_e32 v16, 34, v0
	v_cndmask_b32_e32 v15, -1, v15, vcc
	v_cmp_ge_u32_e32 vcc, v16, v4
	v_cmp_lt_u32_e64 s[0:1], v16, v5
	v_sub_u32_e32 v16, v16, v205
	v_med3_i32 v16, v16, -15, 15
	v_add_u32_e32 v16, 15, v16
	s_and_b64 vcc, vcc, s[0:1]
	v_or_b32_e32 v17, 35, v0
	v_cndmask_b32_e32 v16, -1, v16, vcc
	v_cmp_ge_u32_e32 vcc, v17, v4
	v_cmp_lt_u32_e64 s[0:1], v17, v5
	v_sub_u32_e32 v4, v17, v205
	v_or_b32_e32 v17, 48, v0
	v_med3_i32 v4, v4, -15, 15
	v_sub_u32_e32 v18, v17, v205
	v_add_u32_e32 v4, 15, v4
	s_and_b64 vcc, vcc, s[0:1]
	v_min_i32_e32 v18, 15, v18
	v_cndmask_b32_e32 v4, -1, v4, vcc
	v_add_u32_e32 v18, 15, v18
	v_cmp_lt_u32_e32 vcc, v17, v5
	v_and_b32_e32 v179, 63, v1
	v_or_b32_e32 v22, 0x1c0, v179
	v_cndmask_b32_e32 v17, -1, v18, vcc
	v_or_b32_e32 v18, 49, v0
	v_sub_u32_e32 v19, v18, v205
	v_min_i32_e32 v19, 15, v19
	v_add_u32_e32 v19, 15, v19
	v_cmp_lt_u32_e32 vcc, v18, v5
	v_lshrrev_b32_e32 v23, 3, v22
	v_mul_u32_u24_e32 v24, 0x910, v23
	v_cndmask_b32_e32 v18, -1, v19, vcc
	v_or_b32_e32 v19, 50, v0
	v_sub_u32_e32 v20, v19, v205
	v_min_i32_e32 v20, 15, v20
	v_add_u32_e32 v20, 15, v20
	v_cmp_lt_u32_e32 vcc, v19, v5
	s_add_i32 s23, s26, 1
	s_cmp_lg_u32 s26, 3
	v_cndmask_b32_e32 v19, -1, v20, vcc
	v_or_b32_e32 v20, 51, v0
	v_sub_u32_e32 v21, v20, v205
	v_min_i32_e32 v21, 15, v21
	v_cmp_lt_u32_e32 vcc, v20, v5
	v_lshlrev_b32_e32 v20, 3, v1
	v_add_u32_e32 v21, 15, v21
	v_and_b32_e32 v20, 56, v20
	v_cndmask_b32_e32 v5, -1, v21, vcc
	v_or_b32_e32 v21, 0x200, v20
	v_add_lshl_u32 v108, v24, v21, 1
	v_or_b32_e32 v24, 0x180, v179
	v_lshrrev_b32_e32 v24, 3, v24
	v_mul_u32_u24_e32 v25, 0x910, v24
	v_add_lshl_u32 v110, v25, v21, 1
	v_or_b32_e32 v25, 0x140, v179
	v_lshrrev_b32_e32 v25, 3, v25
	v_mul_u32_u24_e32 v26, 0x910, v25
	v_add_lshl_u32 v112, v26, v21, 1
	v_or_b32_e32 v26, 0x100, v179
	v_lshrrev_b32_e32 v26, 3, v26
	s_cselect_b32 s0, s23, 3
	v_mul_u32_u24_e32 v27, 0x910, v26
	s_cmp_gt_u32 s0, 1
	v_add_lshl_u32 v114, v27, v21, 1
	v_or_b32_e32 v27, 0xc0, v179
	s_cselect_b64 s[38:39], -1, 0
	v_lshrrev_b32_e32 v27, 3, v27
	v_writelane_b32 v254, s38, 23
	v_mul_u32_u24_e32 v28, 0x910, v27
	s_movk_i32 s1, 0x1d1
	v_writelane_b32 v254, s39, 24
	v_add_lshl_u32 v116, v28, v21, 1
	v_or_b32_e32 v28, 0x80, v179
	s_ashr_i32 s76, s22, 8
	v_cmp_gt_u32_e64 s[22:23], s1, v22
	v_lshrrev_b32_e32 v28, 3, v28
	s_cmp_lt_u32 s26, 2
	v_writelane_b32 v254, s22, 51
	v_mul_u32_u24_e32 v29, 0x910, v28
	v_add_lshl_u32 v118, v29, v21, 1
	v_writelane_b32 v254, s23, 52
	s_cselect_b64 s[22:23], -1, 0
	s_cmp_gt_u32 s26, 1
	v_or_b32_e32 v29, 64, v179
	s_cselect_b64 s[26:27], -1, 0
	s_cmp_gt_u32 s0, 2
	v_lshrrev_b32_e32 v29, 3, v29
	s_cselect_b64 s[0:1], -1, 0
	v_mul_u32_u24_e32 v30, 0x910, v29
	v_writelane_b32 v254, s0, 62
	v_add_lshl_u32 v120, v30, v21, 1
	v_bfe_u32 v30, v1, 3, 3
	v_and_b32_e32 v1, 48, v1
	v_writelane_b32 v254, s1, 63
	s_movk_i32 s0, 0x1220
	v_mad_u32_u24 v126, v3, s0, v1
	v_mov_b32_e32 v127, v169
	s_mov_b64 s[0:1], 0x12200
	v_lshl_add_u64 v[128:129], v[126:127], 0, s[0:1]
	s_mov_b64 s[0:1], 0x24400
	v_lshl_add_u64 v[130:131], v[126:127], 0, s[0:1]
	s_mov_b64 s[0:1], 0x36600
	v_readlane_b32 s74, v254, 21
	v_lshlrev_b32_e32 v168, 2, v179
	v_lshl_add_u64 v[132:133], v[126:127], 0, s[0:1]
	v_readlane_b32 s75, v254, 22
	s_add_u32 s0, s78, s74
	v_add_u32_e32 v206, s40, v168
	v_lshl_add_u64 v[124:125], s[2:3], 0, v[168:169]
	v_add_u32_e32 v168, 0x200, v126
	s_addc_u32 s1, s79, s75
	v_lshl_add_u64 v[134:135], s[0:1], 0, v[168:169]
	v_add_u32_e32 v168, 0x12400, v126
	v_lshl_add_u64 v[136:137], s[0:1], 0, v[168:169]
	v_add_u32_e32 v168, 0x24600, v126
	s_lshl_b32 s2, s76, 6
	v_lshl_add_u64 v[138:139], s[0:1], 0, v[168:169]
	v_add_u32_e32 v168, 0x36800, v126
	v_writelane_b32 v255, s2, 0
	v_lshl_add_u64 v[140:141], s[0:1], 0, v[168:169]
	s_movk_i32 s2, 0x910
	v_readlane_b32 s0, v253, 48
	v_mad_u32_u24 v1, v30, s2, v20
	s_add_u32 s0, s0, s74
	v_readlane_b32 s1, v253, 49
	v_lshl_add_u32 v168, v1, 1, v171
	s_addc_u32 s1, s1, s75
	v_mad_u32_u24 v1, v29, s2, v20
	v_lshl_add_u64 v[142:143], s[0:1], 0, v[168:169]
	v_lshl_add_u32 v168, v1, 1, v171
	v_mad_u32_u24 v1, v28, s2, v20
	v_lshl_add_u64 v[144:145], s[0:1], 0, v[168:169]
	v_lshl_add_u32 v168, v1, 1, v171
	v_mad_u32_u24 v1, v27, s2, v20
	v_lshl_add_u64 v[146:147], s[0:1], 0, v[168:169]
	v_lshl_add_u32 v168, v1, 1, v171
	v_mad_u32_u24 v1, v26, s2, v20
	v_lshl_add_u64 v[148:149], s[0:1], 0, v[168:169]
	v_lshl_add_u32 v168, v1, 1, v171
	v_mad_u32_u24 v1, v25, s2, v20
	v_lshl_add_u64 v[150:151], s[0:1], 0, v[168:169]
	v_lshl_add_u32 v168, v1, 1, v171
	v_mad_u32_u24 v1, v24, s2, v20
	v_lshl_add_u64 v[152:153], s[0:1], 0, v[168:169]
	v_lshl_add_u32 v168, v1, 1, v171
	v_mad_u32_u24 v1, v23, s2, v20
	v_mul_u32_u24_e32 v31, 0x910, v30
	v_lshlrev_b32_e32 v2, 3, v2
	v_lshl_add_u64 v[154:155], s[0:1], 0, v[168:169]
	v_lshl_add_u32 v168, v1, 1, v171
	v_mov_b32_e32 v84, 0
	v_add_lshl_u32 v122, v21, v31, 1
	v_mov_b32_e32 v123, v169
	v_mov_b32_e32 v121, v169
	v_mov_b32_e32 v119, v169
	v_mov_b32_e32 v117, v169
	v_mov_b32_e32 v115, v169
	v_mov_b32_e32 v113, v169
	v_mov_b32_e32 v111, v169
	v_mov_b32_e32 v109, v169
	v_cmp_lt_i32_e64 s[42:43], -1, v6
	v_cmp_lt_i32_e64 s[44:45], -1, v7
	v_cmp_lt_i32_e64 s[46:47], -1, v8
	v_cmp_lt_i32_e64 s[48:49], -1, v9
	v_cmp_lt_i32_e64 s[50:51], -1, v10
	v_cmp_lt_i32_e64 s[52:53], -1, v11
	v_cmp_lt_i32_e64 s[54:55], -1, v12
	v_cmp_lt_i32_e64 s[56:57], -1, v13
	v_cmp_lt_i32_e64 s[58:59], -1, v14
	v_cmp_lt_i32_e64 s[60:61], -1, v15
	v_cmp_lt_i32_e64 s[62:63], -1, v16
	v_cmp_lt_i32_e64 s[64:65], -1, v4
	v_cmp_lt_i32_e64 s[66:67], -1, v17
	v_cmp_lt_i32_e64 s[68:69], -1, v18
	v_cmp_lt_i32_e64 s[70:71], -1, v19
	v_cmp_lt_i32_e64 s[72:73], -1, v5
	s_mov_b32 s41, s34
	v_writelane_b32 v254, s76, 31
	v_lshl_add_u64 v[156:157], s[0:1], 0, v[168:169]
	v_lshlrev_b32_e32 v207, 2, v6
	v_lshlrev_b32_e32 v208, 2, v7
	v_lshlrev_b32_e32 v209, 2, v8
	v_lshlrev_b32_e32 v210, 2, v9
	v_lshlrev_b32_e32 v211, 2, v10
	v_lshlrev_b32_e32 v212, 2, v11
	v_lshlrev_b32_e32 v213, 2, v12
	v_lshlrev_b32_e32 v214, 2, v13
	v_lshlrev_b32_e32 v215, 2, v14
	v_lshlrev_b32_e32 v216, 2, v15
	v_lshlrev_b32_e32 v217, 2, v16
	v_lshlrev_b32_e32 v218, 2, v4
	v_lshlrev_b32_e32 v219, 2, v17
	v_lshlrev_b32_e32 v220, 2, v18
	v_lshlrev_b32_e32 v221, 2, v19
	v_lshlrev_b32_e32 v222, 2, v5
	v_lshlrev_b32_e32 v168, 1, v2
	v_lshlrev_b32_e32 v158, 1, v0
	v_mov_b32_e32 v85, v84
	v_mov_b32_e32 v86, v84
	v_mov_b32_e32 v87, v84
	v_mov_b32_e32 v80, v84
	v_mov_b32_e32 v81, v84
	v_mov_b32_e32 v82, v84
	v_mov_b32_e32 v83, v84
	v_mov_b32_e32 v76, v84
	v_mov_b32_e32 v77, v84
	v_mov_b32_e32 v78, v84
	v_mov_b32_e32 v79, v84
	v_mov_b32_e32 v64, v84
	v_mov_b32_e32 v65, v84
	v_mov_b32_e32 v66, v84
	v_mov_b32_e32 v67, v84
	s_branch .LBB0_694
.LBB0_693:
	s_waitcnt vmcnt(1)
	ds_bpermute_b32 v68, v223, v159
	v_readlane_b32 s0, v254, 57
	v_readlane_b32 s1, v254, 58
	v_readlane_b32 s41, v255, 12
	s_cmp_eq_u32 s41, 0
	s_cbranch_scc1 .Lna_old_inc
	v_readlane_b32 s41, v255, 11
	s_add_i32 s41, s41, 1
	v_writelane_b32 v255, s41, 11
	s_lshr_b32 s34, s41, 2
	s_lshl_b32 s34, s34, 7
	s_and_b32 s41, s41, 3
	s_lshl_b32 s41, s41, 5
	s_or_b32 s34, s34, s41
	v_readlane_b32 s41, v255, 10
	s_add_i32 s34, s34, s41
	v_readlane_b32 s41, v255, 11
	s_cmp_ge_u32 s41, 8
	s_cselect_b32 s34, 0x800, s34
	s_mov_b32 s41, s34
	s_branch .Lna_inc_done
.Lna_old_inc:
	s_add_i32 s34, s34, 1
	s_add_i32 s41, s41, 1
.Lna_inc_done:
	s_waitcnt lgkmcnt(0)
	v_add_f32_e32 v70, v159, v68
	ds_bpermute_b32 v71, v242, v70
	v_lshlrev_b64 v[68:69], 11, v[160:161]
	v_lshl_add_u64 v[68:69], s[0:1], 0, v[68:69]
	v_mov_b32_e32 v159, v169
	v_lshl_add_u64 v[68:69], s[20:21], 1, v[68:69]
	s_waitcnt lgkmcnt(0)
	v_add_f32_e32 v70, v70, v71
	v_div_scale_f32 v71, s[0:1], v70, v70, 1.0
	s_waitcnt vmcnt(0)
	v_rcp_f32_e32 v72, v71
	v_div_scale_f32 v73, vcc, 1.0, v70, 1.0
	v_lshl_add_u64 v[68:69], v[68:69], 0, v[158:159]
	v_fma_f32 v74, -v71, v72, 1.0
	v_fmac_f32_e32 v72, v74, v72
	v_mul_f32_e32 v74, v73, v72
	v_fma_f32 v75, -v71, v74, v73
	v_fmac_f32_e32 v74, v75, v72
	v_fma_f32 v71, -v71, v74, v73
	v_div_fmas_f32 v71, v71, v72, v74
	v_div_fixup_f32 v72, v71, v70, 1.0
	v_mul_f32_e32 v70, v100, v72
	v_mul_f32_e32 v71, v101, v72
	v_cvt_pk_bf16_f32 v70, v70, v71
	v_mul_f32_e32 v71, v103, v72
	v_mul_f32_e32 v73, v102, v72
	v_cvt_pk_bf16_f32 v71, v73, v71
	global_store_dwordx2 v[68:69], v[70:71], off
	v_mul_f32_e32 v70, v96, v72
	v_mul_f32_e32 v71, v97, v72
	v_cvt_pk_bf16_f32 v70, v70, v71
	v_mul_f32_e32 v71, v98, v72
	v_mul_f32_e32 v73, v99, v72
	v_cvt_pk_bf16_f32 v71, v71, v73
	global_store_dwordx2 v[68:69], v[70:71], off offset:32
	v_mul_f32_e32 v70, v92, v72
	v_mul_f32_e32 v71, v93, v72
	v_cvt_pk_bf16_f32 v70, v70, v71
	v_mul_f32_e32 v71, v94, v72
	v_mul_f32_e32 v73, v95, v72
	v_cvt_pk_bf16_f32 v71, v71, v73
	global_store_dwordx2 v[68:69], v[70:71], off offset:64
	v_mul_f32_e32 v70, v88, v72
	v_mul_f32_e32 v71, v89, v72
	v_readlane_b32 s0, v254, 59
	v_cvt_pk_bf16_f32 v70, v70, v71
	v_mul_f32_e32 v71, v90, v72
	s_cmp_ge_i32 s34, s0
	v_mul_f32_e32 v72, v91, v72
	v_cvt_pk_bf16_f32 v71, v71, v72
	global_store_dwordx2 v[68:69], v[70:71], off offset:96
	s_cbranch_scc1 .LBB0_1801
.LBB0_694:
	s_lshr_b32 s0, s34, 6
	s_and_b32 s0, s0, 2
	v_readlane_b32 s1, v254, 31
	s_add_i32 s0, s0, s1
	s_mul_i32 s2, s0, 0x1d1
	s_ashr_i32 s3, s2, 31
	v_lshl_add_u64 v[68:69], s[2:3], 2, v[124:125]
	global_load_dword v70, v[68:69], off
	global_load_dword v71, v[68:69], off offset:256
	global_load_dword v72, v[68:69], off offset:512
	global_load_dword v73, v[68:69], off offset:768
	global_load_dword v74, v[68:69], off offset:1024
	global_load_dword v75, v[68:69], off offset:1280
	global_load_dword v76, v[68:69], off offset:1536
	s_mov_b64 s[2:3], exec
	v_readlane_b32 s20, v254, 51
	v_readlane_b32 s21, v254, 52
	s_and_b64 s[20:21], s[2:3], s[20:21]
	s_movk_i32 s74, 0x1220
	s_mov_b64 exec, s[20:21]
	global_load_dword v77, v[68:69], off offset:1792
	s_mov_b64 exec, s[2:3]
	s_waitcnt vmcnt(0)
	v_mul_f32_e32 v70, 0x3fb8aa3b, v70
	v_mul_f32_e32 v71, 0x3fb8aa3b, v71
	v_mul_f32_e32 v72, 0x3fb8aa3b, v72
	v_mul_f32_e32 v73, 0x3fb8aa3b, v73
	v_mul_f32_e32 v74, 0x3fb8aa3b, v74
	v_mul_f32_e32 v75, 0x3fb8aa3b, v75
	v_mul_f32_e32 v76, 0x3fb8aa3b, v76
	ds_write2st64_b32 v206, v70, v71 offset0:33 offset1:34
	ds_write2st64_b32 v206, v72, v73 offset0:35 offset1:36
	ds_write2st64_b32 v206, v74, v75 offset0:37 offset1:38
	ds_write_b32 v206, v76 offset:9984
	s_mov_b64 exec, s[20:21]
	v_mul_f32_e32 v77, 0x3fb8aa3b, v77
	ds_write_b32 v206, v77 offset:10240

.LBB0_1081:
	s_mov_b32 s46, 0x66666667
	v_mul_hi_i32 v8, v80, s46
	v_lshrrev_b32_e32 v9, 31, v8
	v_ashrrev_i32_e32 v8, 5, v8
	v_add_u32_e32 v8, v8, v9
	s_movk_i32 s46, 0xf600
	v_mul_lo_u32 v81, v8, s46
	v_add3_u32 v10, v5, v79, v81
	s_movk_i32 s46, 0x90f
	v_cmp_lt_i32_e64 s[48:49], s46, v10
	v_lshlrev_b32_e32 v8, 6, v8
	v_ashrrev_i32_e32 v11, 31, v10
	v_lshl_add_u64 v[10:11], v[10:11], 2, s[26:27]
	v_or_b32_e32 v134, v8, v2
	v_mad_i64_i32 v[166:167], s[54:55], v134, s36, v[10:11]
	s_mov_b32 s70, 0x4880
	s_mov_b32 s71, 0
	v_mov_b64_e32 v[102:103], 0
	v_mov_b64_e32 v[104:105], 0
	v_mov_b64_e32 v[106:107], 0
	v_mov_b64_e32 v[108:109], 0
	v_mov_b64_e32 v[110:111], 0
	v_mov_b64_e32 v[112:113], 0
	v_mov_b64_e32 v[114:115], 0
	v_mov_b64_e32 v[116:117], 0
	v_mov_b64_e32 v[118:119], 0
	v_mov_b64_e32 v[120:121], 0
	v_mov_b64_e32 v[122:123], 0
	v_mov_b64_e32 v[124:125], 0
	v_mov_b64_e32 v[126:127], 0
	v_mov_b64_e32 v[128:129], 0
	v_mov_b64_e32 v[130:131], 0
	v_mov_b64_e32 v[132:133], 0
	s_mov_b64 s[54:55], exec
	s_andn2_b64 exec, exec, s[48:49]
	s_cbranch_execz .Ltr_skip_1081
	global_load_dword v102, v[166:167], off
	v_lshl_add_u64 v[166:167], v[166:167], 0, s[70:71]
	global_load_dword v103, v[166:167], off
	v_lshl_add_u64 v[166:167], v[166:167], 0, s[70:71]
	global_load_dword v104, v[166:167], off
	v_lshl_add_u64 v[166:167], v[166:167], 0, s[70:71]
	global_load_dword v105, v[166:167], off
	v_lshl_add_u64 v[166:167], v[166:167], 0, s[70:71]
	global_load_dword v106, v[166:167], off
	v_lshl_add_u64 v[166:167], v[166:167], 0, s[70:71]
	global_load_dword v107, v[166:167], off
	v_lshl_add_u64 v[166:167], v[166:167], 0, s[70:71]
	global_load_dword v108, v[166:167], off
	v_lshl_add_u64 v[166:167], v[166:167], 0, s[70:71]
	global_load_dword v109, v[166:167], off
	v_lshl_add_u64 v[166:167], v[166:167], 0, s[70:71]
	global_load_dword v110, v[166:167], off
	v_lshl_add_u64 v[166:167], v[166:167], 0, s[70:71]
	global_load_dword v111, v[166:167], off
	v_lshl_add_u64 v[166:167], v[166:167], 0, s[70:71]
	global_load_dword v112, v[166:167], off
	v_lshl_add_u64 v[166:167], v[166:167], 0, s[70:71]
	global_load_dword v113, v[166:167], off
	v_lshl_add_u64 v[166:167], v[166:167], 0, s[70:71]
	global_load_dword v114, v[166:167], off
	v_lshl_add_u64 v[166:167], v[166:167], 0, s[70:71]
	global_load_dword v115, v[166:167], off
	v_lshl_add_u64 v[166:167], v[166:167], 0, s[70:71]
	global_load_dword v116, v[166:167], off
	v_lshl_add_u64 v[166:167], v[166:167], 0, s[70:71]
	global_load_dword v117, v[166:167], off
	v_lshl_add_u64 v[166:167], v[166:167], 0, s[70:71]
	global_load_dword v118, v[166:167], off
	v_lshl_add_u64 v[166:167], v[166:167], 0, s[70:71]
	global_load_dword v119, v[166:167], off
	v_lshl_add_u64 v[166:167], v[166:167], 0, s[70:71]
	global_load_dword v120, v[166:167], off
	v_lshl_add_u64 v[166:167], v[166:167], 0, s[70:71]
	global_load_dword v121, v[166:167], off
	v_lshl_add_u64 v[166:167], v[166:167], 0, s[70:71]
	global_load_dword v122, v[166:167], off
	v_lshl_add_u64 v[166:167], v[166:167], 0, s[70:71]
	global_load_dword v123, v[166:167], off
	v_lshl_add_u64 v[166:167], v[166:167], 0, s[70:71]
	global_load_dword v124, v[166:167], off
	v_lshl_add_u64 v[166:167], v[166:167], 0, s[70:71]
	global_load_dword v125, v[166:167], off
	v_lshl_add_u64 v[166:167], v[166:167], 0, s[70:71]
	global_load_dword v126, v[166:167], off
	v_lshl_add_u64 v[166:167], v[166:167], 0, s[70:71]
	global_load_dword v127, v[166:167], off
	v_lshl_add_u64 v[166:167], v[166:167], 0, s[70:71]
	global_load_dword v128, v[166:167], off
	v_lshl_add_u64 v[166:167], v[166:167], 0, s[70:71]
	global_load_dword v129, v[166:167], off
	v_lshl_add_u64 v[166:167], v[166:167], 0, s[70:71]
	global_load_dword v130, v[166:167], off
	v_lshl_add_u64 v[166:167], v[166:167], 0, s[70:71]
	global_load_dword v131, v[166:167], off
	v_lshl_add_u64 v[166:167], v[166:167], 0, s[70:71]
	global_load_dword v132, v[166:167], off
	v_lshl_add_u64 v[166:167], v[166:167], 0, s[70:71]
	global_load_dword v133, v[166:167], off

.LBB0_1208:
	s_or_b64 exec, exec, s[24:25]
	s_xor_b64 s[24:25], s[2:3], -1
	s_mov_b64 s[20:21], 0
	s_lshl_b64 s[50:51], s[34:35], 20
	s_cmp_eq_u32 s22, 0x800
	s_cselect_b32 s70, 0x300, 0
	v_add_u32_e32 v170, s70, v28
	v_cmp_le_i32_e32 vcc, s22, v170
	v_subrev_u32_e32 v174, s22, v170
	s_nop 0
	v_cndmask_b32_e32 v170, v170, v174, vcc
	v_cmp_gt_i32_e32 vcc, 0x200, v170
	s_and_saveexec_b64 s[2:3], vcc
	s_cbranch_execz .LBB0_1243
	s_add_u32 s23, s92, s20
	s_addc_u32 s26, s93, s21
	s_lshl_b64 s[20:21], s[50:51], 2
	s_add_u32 s20, s23, s20
	s_addc_u32 s21, s26, s21
	v_lshl_add_u64 v[6:7], s[0:1], 0, v[168:169]
	s_mov_b64 s[26:27], 0x500000
	v_lshl_add_u64 v[6:7], v[6:7], 0, s[26:27]
	v_lshlrev_b32_e32 v12, 5, v170
	s_lshl_b32 s23, s22, 5
	s_mov_b64 s[26:27], 0
	v_mov_b32_e32 v13, v170
	s_branch .LBB0_1211

.LBB0_1211:
	v_ashrrev_i32_e32 v8, 31, v13
	v_lshrrev_b32_e32 v8, 27, v8
	v_add_u32_e32 v8, v13, v8
	v_ashrrev_i32_e32 v8, 5, v8
	v_lshlrev_b32_e32 v9, 10, v8
	v_add_u32_e32 v10, v5, v12
	v_sub_u32_e32 v10, v10, v9
	v_cmp_lt_i32_e32 vcc, s33, v10
	v_lshlrev_b32_e32 v8, 6, v8
	v_ashrrev_i32_e32 v11, 31, v10
	v_lshl_add_u64 v[10:11], v[10:11], 2, s[20:21]
	v_or_b32_e32 v134, v8, v2
	v_ashrrev_i32_e32 v135, 31, v134
	v_lshlrev_b64 v[166:167], 12, v[134:135]
	v_lshl_add_u64 v[166:167], v[10:11], 0, v[166:167]
	s_mov_b32 s70, 0x2000
	s_mov_b32 s71, 0
	v_mov_b64_e32 v[102:103], 0
	v_mov_b64_e32 v[104:105], 0
	v_mov_b64_e32 v[106:107], 0
	v_mov_b64_e32 v[108:109], 0
	v_mov_b64_e32 v[110:111], 0
	v_mov_b64_e32 v[112:113], 0
	v_mov_b64_e32 v[114:115], 0
	v_mov_b64_e32 v[116:117], 0
	v_mov_b64_e32 v[118:119], 0
	v_mov_b64_e32 v[120:121], 0
	v_mov_b64_e32 v[122:123], 0
	v_mov_b64_e32 v[124:125], 0
	v_mov_b64_e32 v[126:127], 0
	v_mov_b64_e32 v[128:129], 0
	v_mov_b64_e32 v[130:131], 0
	v_mov_b64_e32 v[132:133], 0
	s_mov_b64 s[46:47], exec
	s_andn2_b64 exec, exec, vcc
	s_cbranch_execz .Ltr_skip_1211
	global_load_dword v102, v[166:167], off
	v_lshl_add_u64 v[166:167], v[166:167], 0, s[70:71]
	global_load_dword v103, v[166:167], off
	v_lshl_add_u64 v[166:167], v[166:167], 0, s[70:71]
	global_load_dword v104, v[166:167], off
	v_lshl_add_u64 v[166:167], v[166:167], 0, s[70:71]
	global_load_dword v105, v[166:167], off
	v_lshl_add_u64 v[166:167], v[166:167], 0, s[70:71]
	global_load_dword v106, v[166:167], off
	v_lshl_add_u64 v[166:167], v[166:167], 0, s[70:71]
	global_load_dword v107, v[166:167], off
	v_lshl_add_u64 v[166:167], v[166:167], 0, s[70:71]
	global_load_dword v108, v[166:167], off
	v_lshl_add_u64 v[166:167], v[166:167], 0, s[70:71]
	global_load_dword v109, v[166:167], off
	v_lshl_add_u64 v[166:167], v[166:167], 0, s[70:71]
	global_load_dword v110, v[166:167], off
	v_lshl_add_u64 v[166:167], v[166:167], 0, s[70:71]
	global_load_dword v111, v[166:167], off
	v_lshl_add_u64 v[166:167], v[166:167], 0, s[70:71]
	global_load_dword v112, v[166:167], off
	v_lshl_add_u64 v[166:167], v[166:167], 0, s[70:71]
	global_load_dword v113, v[166:167], off
	v_lshl_add_u64 v[166:167], v[166:167], 0, s[70:71]
	global_load_dword v114, v[166:167], off
	v_lshl_add_u64 v[166:167], v[166:167], 0, s[70:71]
	global_load_dword v115, v[166:167], off
	v_lshl_add_u64 v[166:167], v[166:167], 0, s[70:71]
	global_load_dword v116, v[166:167], off
	v_lshl_add_u64 v[166:167], v[166:167], 0, s[70:71]
	global_load_dword v117, v[166:167], off
	v_lshl_add_u64 v[166:167], v[166:167], 0, s[70:71]
	global_load_dword v118, v[166:167], off
	v_lshl_add_u64 v[166:167], v[166:167], 0, s[70:71]
	global_load_dword v119, v[166:167], off
	v_lshl_add_u64 v[166:167], v[166:167], 0, s[70:71]
	global_load_dword v120, v[166:167], off
	v_lshl_add_u64 v[166:167], v[166:167], 0, s[70:71]
	global_load_dword v121, v[166:167], off
	v_lshl_add_u64 v[166:167], v[166:167], 0, s[70:71]
	global_load_dword v122, v[166:167], off
	v_lshl_add_u64 v[166:167], v[166:167], 0, s[70:71]
	global_load_dword v123, v[166:167], off
	v_lshl_add_u64 v[166:167], v[166:167], 0, s[70:71]
	global_load_dword v124, v[166:167], off
	v_lshl_add_u64 v[166:167], v[166:167], 0, s[70:71]
	global_load_dword v125, v[166:167], off
	v_lshl_add_u64 v[166:167], v[166:167], 0, s[70:71]
	global_load_dword v126, v[166:167], off
	v_lshl_add_u64 v[166:167], v[166:167], 0, s[70:71]
	global_load_dword v127, v[166:167], off
	v_lshl_add_u64 v[166:167], v[166:167], 0, s[70:71]
	global_load_dword v128, v[166:167], off
	v_lshl_add_u64 v[166:167], v[166:167], 0, s[70:71]
	global_load_dword v129, v[166:167], off
	v_lshl_add_u64 v[166:167], v[166:167], 0, s[70:71]
	global_load_dword v130, v[166:167], off
	v_lshl_add_u64 v[166:167], v[166:167], 0, s[70:71]
	global_load_dword v131, v[166:167], off
	v_lshl_add_u64 v[166:167], v[166:167], 0, s[70:71]
	global_load_dword v132, v[166:167], off
	v_lshl_add_u64 v[166:167], v[166:167], 0, s[70:71]
	global_load_dword v133, v[166:167], off

.LBB0_1243:
	s_or_b64 exec, exec, s[2:3]
	s_mov_b64 s[20:21], 0
	s_mov_b64 s[46:47], 0
	s_lshl_b32 s26, s34, 10
	s_mov_b32 s27, s35
	s_cmp_eq_u32 s22, 0x800
	s_cselect_b32 s70, 0x100, 0
	v_add_u32_e32 v170, s70, v28
	v_cmp_le_i32_e32 vcc, s22, v170
	v_subrev_u32_e32 v174, s22, v170
	s_nop 0
	v_cndmask_b32_e32 v170, v170, v174, vcc
	v_cmp_gt_i32_e32 vcc, 0x200, v170
	s_and_saveexec_b64 s[2:3], vcc
	s_cbranch_execz .LBB0_1374
	v_readlane_b32 s52, v252, 16
	v_readlane_b32 s54, v252, 18
	v_readlane_b32 s55, v252, 19
	s_add_u32 s23, s54, s20
	s_addc_u32 s48, s55, s21
	s_lshl_b64 s[20:21], s[50:51], 2
	s_add_u32 s20, s23, s20
	s_addc_u32 s21, s48, s21
	s_add_u32 s23, s94, s46
	s_addc_u32 s48, s95, s47
	s_lshl_b64 s[46:47], s[26:27], 2
	v_readlane_b32 s53, v252, 17
	s_add_u32 s52, s23, s46
	s_addc_u32 s53, s48, s47
	v_lshl_add_u64 v[6:7], s[0:1], 0, v[168:169]
	s_mov_b64 s[46:47], 0x700000
	v_lshl_add_u64 v[6:7], v[6:7], 0, s[46:47]
	v_lshlrev_b32_e32 v79, 5, v170
	s_lshl_b32 s23, s22, 5
	s_mov_b64 s[54:55], 0
	v_mov_b32_e32 v80, v170
	v_readlane_b32 s56, v252, 20
	v_readlane_b32 s57, v252, 21
	v_readlane_b32 s58, v252, 22
	v_readlane_b32 s59, v252, 23
	v_readlane_b32 s60, v252, 24
	v_readlane_b32 s61, v252, 25
	v_readlane_b32 s62, v252, 26
	v_readlane_b32 s63, v252, 27
	v_readlane_b32 s64, v252, 28
	v_readlane_b32 s65, v252, 29
	v_readlane_b32 s66, v252, 30
	v_readlane_b32 s67, v252, 31
	s_branch .LBB0_1247

.LBB0_1247:
	v_ashrrev_i32_e32 v8, 31, v80
	v_lshrrev_b32_e32 v8, 27, v8
	v_add_u32_e32 v8, v80, v8
	v_ashrrev_i32_e32 v8, 5, v8
	v_lshlrev_b32_e32 v81, 10, v8
	v_add_u32_e32 v9, v5, v79
	v_sub_u32_e32 v10, v9, v81
	v_cmp_lt_i32_e64 s[48:49], s33, v10
	v_lshlrev_b32_e32 v8, 6, v8
	v_ashrrev_i32_e32 v11, 31, v10
	v_lshl_add_u64 v[10:11], v[10:11], 2, s[20:21]
	v_sub_u32_e32 v12, 0, v81
	v_or_b32_e32 v134, v8, v2
	v_ashrrev_i32_e32 v135, 31, v134
	v_lshlrev_b64 v[166:167], 12, v[134:135]
	v_lshl_add_u64 v[166:167], v[10:11], 0, v[166:167]
	s_mov_b32 s70, 0x2000
	s_mov_b32 s71, 0
	v_mov_b64_e32 v[102:103], 0
	v_mov_b64_e32 v[104:105], 0
	v_mov_b64_e32 v[106:107], 0
	v_mov_b64_e32 v[108:109], 0
	v_mov_b64_e32 v[110:111], 0
	v_mov_b64_e32 v[112:113], 0
	v_mov_b64_e32 v[114:115], 0
	v_mov_b64_e32 v[116:117], 0
	v_mov_b64_e32 v[118:119], 0
	v_mov_b64_e32 v[120:121], 0
	v_mov_b64_e32 v[122:123], 0
	v_mov_b64_e32 v[124:125], 0
	v_mov_b64_e32 v[126:127], 0
	v_mov_b64_e32 v[128:129], 0
	v_mov_b64_e32 v[130:131], 0
	v_mov_b64_e32 v[132:133], 0
	s_mov_b64 s[56:57], exec
	s_andn2_b64 exec, exec, s[48:49]
	s_cbranch_execz .Ltr_skip_1247
	global_load_dword v102, v[166:167], off
	v_lshl_add_u64 v[166:167], v[166:167], 0, s[70:71]
	global_load_dword v103, v[166:167], off
	v_lshl_add_u64 v[166:167], v[166:167], 0, s[70:71]
	global_load_dword v104, v[166:167], off
	v_lshl_add_u64 v[166:167], v[166:167], 0, s[70:71]
	global_load_dword v105, v[166:167], off
	v_lshl_add_u64 v[166:167], v[166:167], 0, s[70:71]
	global_load_dword v106, v[166:167], off
	v_lshl_add_u64 v[166:167], v[166:167], 0, s[70:71]
	global_load_dword v107, v[166:167], off
	v_lshl_add_u64 v[166:167], v[166:167], 0, s[70:71]
	global_load_dword v108, v[166:167], off
	v_lshl_add_u64 v[166:167], v[166:167], 0, s[70:71]
	global_load_dword v109, v[166:167], off
	v_lshl_add_u64 v[166:167], v[166:167], 0, s[70:71]
	global_load_dword v110, v[166:167], off
	v_lshl_add_u64 v[166:167], v[166:167], 0, s[70:71]
	global_load_dword v111, v[166:167], off
	v_lshl_add_u64 v[166:167], v[166:167], 0, s[70:71]
	global_load_dword v112, v[166:167], off
	v_lshl_add_u64 v[166:167], v[166:167], 0, s[70:71]
	global_load_dword v113, v[166:167], off
	v_lshl_add_u64 v[166:167], v[166:167], 0, s[70:71]
	global_load_dword v114, v[166:167], off
	v_lshl_add_u64 v[166:167], v[166:167], 0, s[70:71]
	global_load_dword v115, v[166:167], off
	v_lshl_add_u64 v[166:167], v[166:167], 0, s[70:71]
	global_load_dword v116, v[166:167], off
	v_lshl_add_u64 v[166:167], v[166:167], 0, s[70:71]
	global_load_dword v117, v[166:167], off
	v_lshl_add_u64 v[166:167], v[166:167], 0, s[70:71]
	global_load_dword v118, v[166:167], off
	v_lshl_add_u64 v[166:167], v[166:167], 0, s[70:71]
	global_load_dword v119, v[166:167], off
	v_lshl_add_u64 v[166:167], v[166:167], 0, s[70:71]
	global_load_dword v120, v[166:167], off
	v_lshl_add_u64 v[166:167], v[166:167], 0, s[70:71]
	global_load_dword v121, v[166:167], off
	v_lshl_add_u64 v[166:167], v[166:167], 0, s[70:71]
	global_load_dword v122, v[166:167], off
	v_lshl_add_u64 v[166:167], v[166:167], 0, s[70:71]
	global_load_dword v123, v[166:167], off
	v_lshl_add_u64 v[166:167], v[166:167], 0, s[70:71]
	global_load_dword v124, v[166:167], off
	v_lshl_add_u64 v[166:167], v[166:167], 0, s[70:71]
	global_load_dword v125, v[166:167], off
	v_lshl_add_u64 v[166:167], v[166:167], 0, s[70:71]
	global_load_dword v126, v[166:167], off
	v_lshl_add_u64 v[166:167], v[166:167], 0, s[70:71]
	global_load_dword v127, v[166:167], off
	v_lshl_add_u64 v[166:167], v[166:167], 0, s[70:71]
	global_load_dword v128, v[166:167], off
	v_lshl_add_u64 v[166:167], v[166:167], 0, s[70:71]
	global_load_dword v129, v[166:167], off
	v_lshl_add_u64 v[166:167], v[166:167], 0, s[70:71]
	global_load_dword v130, v[166:167], off
	v_lshl_add_u64 v[166:167], v[166:167], 0, s[70:71]
	global_load_dword v131, v[166:167], off
	v_lshl_add_u64 v[166:167], v[166:167], 0, s[70:71]
	global_load_dword v132, v[166:167], off
	v_lshl_add_u64 v[166:167], v[166:167], 0, s[70:71]
	global_load_dword v133, v[166:167], off

.LBB0_1374:
	s_or_b64 exec, exec, s[2:3]
	s_mov_b64 s[20:21], 0
	s_cmp_eq_u32 s22, 0x800
	s_cselect_b32 s70, 0x700, 0
	v_add_u32_e32 v170, s70, v28
	v_cmp_le_i32_e32 vcc, s22, v170
	v_subrev_u32_e32 v174, s22, v170
	s_nop 0
	v_cndmask_b32_e32 v170, v170, v174, vcc
	v_cmp_gt_i32_e32 vcc, 0x200, v170
	s_and_saveexec_b64 s[2:3], vcc
	s_cbranch_execz .LBB0_1409
	v_readlane_b32 s52, v252, 16
	v_readlane_b32 s56, v252, 20
	v_readlane_b32 s57, v252, 21
	s_add_u32 s23, s56, s20
	s_addc_u32 s46, s57, s21
	s_lshl_b64 s[20:21], s[50:51], 2
	s_add_u32 s20, s23, s20
	s_addc_u32 s21, s46, s21
	v_lshl_add_u64 v[6:7], s[0:1], 0, v[168:169]
	s_mov_b64 s[46:47], 0x900000
	v_lshl_add_u64 v[6:7], v[6:7], 0, s[46:47]
	v_lshlrev_b32_e32 v12, 5, v170
	s_lshl_b32 s23, s22, 5
	s_mov_b64 s[46:47], 0
	v_mov_b32_e32 v13, v170
	v_readlane_b32 s53, v252, 17
	v_readlane_b32 s54, v252, 18
	v_readlane_b32 s55, v252, 19
	v_readlane_b32 s58, v252, 22
	v_readlane_b32 s59, v252, 23
	v_readlane_b32 s60, v252, 24
	v_readlane_b32 s61, v252, 25
	v_readlane_b32 s62, v252, 26
	v_readlane_b32 s63, v252, 27
	v_readlane_b32 s64, v252, 28
	v_readlane_b32 s65, v252, 29
	v_readlane_b32 s66, v252, 30
	v_readlane_b32 s67, v252, 31
	s_branch .LBB0_1377

.LBB0_1377:
	v_ashrrev_i32_e32 v8, 31, v13
	v_lshrrev_b32_e32 v8, 27, v8
	v_add_u32_e32 v8, v13, v8
	v_ashrrev_i32_e32 v8, 5, v8
	v_lshlrev_b32_e32 v9, 10, v8
	v_add_u32_e32 v10, v5, v12
	v_sub_u32_e32 v10, v10, v9
	v_cmp_lt_i32_e32 vcc, s33, v10
	v_lshlrev_b32_e32 v8, 6, v8
	v_ashrrev_i32_e32 v11, 31, v10
	v_lshl_add_u64 v[10:11], v[10:11], 2, s[20:21]
	v_or_b32_e32 v134, v8, v2
	v_ashrrev_i32_e32 v135, 31, v134
	v_lshlrev_b64 v[166:167], 12, v[134:135]
	v_lshl_add_u64 v[166:167], v[10:11], 0, v[166:167]
	s_mov_b32 s70, 0x2000
	s_mov_b32 s71, 0
	v_mov_b64_e32 v[102:103], 0
	v_mov_b64_e32 v[104:105], 0
	v_mov_b64_e32 v[106:107], 0
	v_mov_b64_e32 v[108:109], 0
	v_mov_b64_e32 v[110:111], 0
	v_mov_b64_e32 v[112:113], 0
	v_mov_b64_e32 v[114:115], 0
	v_mov_b64_e32 v[116:117], 0
	v_mov_b64_e32 v[118:119], 0
	v_mov_b64_e32 v[120:121], 0
	v_mov_b64_e32 v[122:123], 0
	v_mov_b64_e32 v[124:125], 0
	v_mov_b64_e32 v[126:127], 0
	v_mov_b64_e32 v[128:129], 0
	v_mov_b64_e32 v[130:131], 0
	v_mov_b64_e32 v[132:133], 0
	s_mov_b64 s[48:49], exec
	s_andn2_b64 exec, exec, vcc
	s_cbranch_execz .Ltr_skip_1377
	global_load_dword v102, v[166:167], off
	v_lshl_add_u64 v[166:167], v[166:167], 0, s[70:71]
	global_load_dword v103, v[166:167], off
	v_lshl_add_u64 v[166:167], v[166:167], 0, s[70:71]
	global_load_dword v104, v[166:167], off
	v_lshl_add_u64 v[166:167], v[166:167], 0, s[70:71]
	global_load_dword v105, v[166:167], off
	v_lshl_add_u64 v[166:167], v[166:167], 0, s[70:71]
	global_load_dword v106, v[166:167], off
	v_lshl_add_u64 v[166:167], v[166:167], 0, s[70:71]
	global_load_dword v107, v[166:167], off
	v_lshl_add_u64 v[166:167], v[166:167], 0, s[70:71]
	global_load_dword v108, v[166:167], off
	v_lshl_add_u64 v[166:167], v[166:167], 0, s[70:71]
	global_load_dword v109, v[166:167], off
	v_lshl_add_u64 v[166:167], v[166:167], 0, s[70:71]
	global_load_dword v110, v[166:167], off
	v_lshl_add_u64 v[166:167], v[166:167], 0, s[70:71]
	global_load_dword v111, v[166:167], off
	v_lshl_add_u64 v[166:167], v[166:167], 0, s[70:71]
	global_load_dword v112, v[166:167], off
	v_lshl_add_u64 v[166:167], v[166:167], 0, s[70:71]
	global_load_dword v113, v[166:167], off
	v_lshl_add_u64 v[166:167], v[166:167], 0, s[70:71]
	global_load_dword v114, v[166:167], off
	v_lshl_add_u64 v[166:167], v[166:167], 0, s[70:71]
	global_load_dword v115, v[166:167], off
	v_lshl_add_u64 v[166:167], v[166:167], 0, s[70:71]
	global_load_dword v116, v[166:167], off
	v_lshl_add_u64 v[166:167], v[166:167], 0, s[70:71]
	global_load_dword v117, v[166:167], off
	v_lshl_add_u64 v[166:167], v[166:167], 0, s[70:71]
	global_load_dword v118, v[166:167], off
	v_lshl_add_u64 v[166:167], v[166:167], 0, s[70:71]
	global_load_dword v119, v[166:167], off
	v_lshl_add_u64 v[166:167], v[166:167], 0, s[70:71]
	global_load_dword v120, v[166:167], off
	v_lshl_add_u64 v[166:167], v[166:167], 0, s[70:71]
	global_load_dword v121, v[166:167], off
	v_lshl_add_u64 v[166:167], v[166:167], 0, s[70:71]
	global_load_dword v122, v[166:167], off
	v_lshl_add_u64 v[166:167], v[166:167], 0, s[70:71]
	global_load_dword v123, v[166:167], off
	v_lshl_add_u64 v[166:167], v[166:167], 0, s[70:71]
	global_load_dword v124, v[166:167], off
	v_lshl_add_u64 v[166:167], v[166:167], 0, s[70:71]
	global_load_dword v125, v[166:167], off
	v_lshl_add_u64 v[166:167], v[166:167], 0, s[70:71]
	global_load_dword v126, v[166:167], off
	v_lshl_add_u64 v[166:167], v[166:167], 0, s[70:71]
	global_load_dword v127, v[166:167], off
	v_lshl_add_u64 v[166:167], v[166:167], 0, s[70:71]
	global_load_dword v128, v[166:167], off
	v_lshl_add_u64 v[166:167], v[166:167], 0, s[70:71]
	global_load_dword v129, v[166:167], off
	v_lshl_add_u64 v[166:167], v[166:167], 0, s[70:71]
	global_load_dword v130, v[166:167], off
	v_lshl_add_u64 v[166:167], v[166:167], 0, s[70:71]
	global_load_dword v131, v[166:167], off
	v_lshl_add_u64 v[166:167], v[166:167], 0, s[70:71]
	global_load_dword v132, v[166:167], off
	v_lshl_add_u64 v[166:167], v[166:167], 0, s[70:71]
	global_load_dword v133, v[166:167], off

.LBB0_1409:
	s_or_b64 exec, exec, s[2:3]
	s_mov_b64 s[20:21], 0
	s_cmp_eq_u32 s22, 0x800
	s_cselect_b32 s70, 0x500, 0
	v_add_u32_e32 v170, s70, v28
	v_cmp_le_i32_e32 vcc, s22, v170
	v_subrev_u32_e32 v174, s22, v170
	s_nop 0
	v_cndmask_b32_e32 v170, v170, v174, vcc
	v_cmp_gt_i32_e32 vcc, 0x200, v170
	s_and_saveexec_b64 s[2:3], vcc
	s_cbranch_execz .LBB0_1444
	v_readlane_b32 s52, v252, 16
	v_readlane_b32 s58, v252, 22
	v_readlane_b32 s59, v252, 23
	s_add_u32 s23, s58, s20
	s_addc_u32 s46, s59, s21
	s_lshl_b64 s[20:21], s[50:51], 2
	s_add_u32 s20, s23, s20
	s_addc_u32 s21, s46, s21
	v_lshl_add_u64 v[6:7], s[0:1], 0, v[168:169]
	s_mov_b64 s[46:47], 0xb00000
	v_lshl_add_u64 v[6:7], v[6:7], 0, s[46:47]
	v_lshlrev_b32_e32 v12, 5, v170
	s_lshl_b32 s23, s22, 5
	s_mov_b64 s[46:47], 0
	v_mov_b32_e32 v13, v170
	v_readlane_b32 s53, v252, 17
	v_readlane_b32 s54, v252, 18
	v_readlane_b32 s55, v252, 19
	v_readlane_b32 s56, v252, 20
	v_readlane_b32 s57, v252, 21
	v_readlane_b32 s60, v252, 24
	v_readlane_b32 s61, v252, 25
	v_readlane_b32 s62, v252, 26
	v_readlane_b32 s63, v252, 27
	v_readlane_b32 s64, v252, 28
	v_readlane_b32 s65, v252, 29
	v_readlane_b32 s66, v252, 30
	v_readlane_b32 s67, v252, 31
	s_branch .LBB0_1412

.LBB0_1444:
	s_or_b64 exec, exec, s[2:3]
	s_mov_b64 s[20:21], 0
	s_cmp_eq_u32 s22, 0x800
	s_cselect_b32 s70, 0x300, 0
	v_add_u32_e32 v170, s70, v28
	v_cmp_le_i32_e32 vcc, s22, v170
	v_subrev_u32_e32 v174, s22, v170
	s_nop 0
	v_cndmask_b32_e32 v170, v170, v174, vcc
	v_cmp_gt_i32_e32 vcc, 0x200, v170
	s_and_saveexec_b64 s[2:3], vcc
	s_cbranch_execz .LBB0_1479
	v_readlane_b32 s52, v252, 16
	v_readlane_b32 s60, v252, 24
	v_readlane_b32 s61, v252, 25
	s_add_u32 s23, s60, s20
	s_addc_u32 s46, s61, s21
	s_lshl_b64 s[20:21], s[50:51], 2
	s_add_u32 s20, s23, s20
	s_addc_u32 s21, s46, s21
	v_lshl_add_u64 v[6:7], s[0:1], 0, v[168:169]
	s_mov_b64 s[46:47], 0xd00000
	v_lshl_add_u64 v[6:7], v[6:7], 0, s[46:47]
	v_lshlrev_b32_e32 v12, 5, v170
	s_lshl_b32 s23, s22, 5
	s_mov_b64 s[46:47], 0
	v_mov_b32_e32 v13, v170
	v_readlane_b32 s53, v252, 17
	v_readlane_b32 s54, v252, 18
	v_readlane_b32 s55, v252, 19
	v_readlane_b32 s56, v252, 20
	v_readlane_b32 s57, v252, 21
	v_readlane_b32 s58, v252, 22
	v_readlane_b32 s59, v252, 23
	v_readlane_b32 s62, v252, 26
	v_readlane_b32 s63, v252, 27
	v_readlane_b32 s64, v252, 28
	v_readlane_b32 s65, v252, 29
	v_readlane_b32 s66, v252, 30
	v_readlane_b32 s67, v252, 31
	s_branch .LBB0_1447

.LBB0_1483:
	v_ashrrev_i32_e32 v8, 31, v80
	v_lshrrev_b32_e32 v8, 25, v8
	v_add_u32_e32 v8, v80, v8
	v_ashrrev_i32_e32 v8, 7, v8
	v_lshlrev_b32_e32 v81, 12, v8
	v_add_u32_e32 v9, v5, v79
	v_sub_u32_e32 v10, v9, v81
	s_movk_i32 s46, 0xfff
	v_cmp_lt_i32_e64 s[48:49], s46, v10
	v_lshlrev_b32_e32 v8, 6, v8
	v_ashrrev_i32_e32 v11, 31, v10
	v_lshl_add_u64 v[10:11], v[10:11], 2, s[50:51]
	v_sub_u32_e32 v12, 0, v81
	v_or_b32_e32 v134, v8, v2
	v_ashrrev_i32_e32 v135, 31, v134
	v_lshlrev_b64 v[166:167], 14, v[134:135]
	v_lshl_add_u64 v[166:167], v[10:11], 0, v[166:167]
	s_mov_b32 s70, 0x8000
	s_mov_b32 s71, 0
	v_mov_b64_e32 v[102:103], 0
	v_mov_b64_e32 v[104:105], 0
	v_mov_b64_e32 v[106:107], 0
	v_mov_b64_e32 v[108:109], 0
	v_mov_b64_e32 v[110:111], 0
	v_mov_b64_e32 v[112:113], 0
	v_mov_b64_e32 v[114:115], 0
	v_mov_b64_e32 v[116:117], 0
	v_mov_b64_e32 v[118:119], 0
	v_mov_b64_e32 v[120:121], 0
	v_mov_b64_e32 v[122:123], 0
	v_mov_b64_e32 v[124:125], 0
	v_mov_b64_e32 v[126:127], 0
	v_mov_b64_e32 v[128:129], 0
	v_mov_b64_e32 v[130:131], 0
	v_mov_b64_e32 v[132:133], 0
	s_mov_b64 s[54:55], exec
	s_andn2_b64 exec, exec, s[48:49]
	s_cbranch_execz .Ltr_skip_1483
	global_load_dword v102, v[166:167], off
	v_lshl_add_u64 v[166:167], v[166:167], 0, s[70:71]
	global_load_dword v103, v[166:167], off
	v_lshl_add_u64 v[166:167], v[166:167], 0, s[70:71]
	global_load_dword v104, v[166:167], off
	v_lshl_add_u64 v[166:167], v[166:167], 0, s[70:71]
	global_load_dword v105, v[166:167], off
	v_lshl_add_u64 v[166:167], v[166:167], 0, s[70:71]
	global_load_dword v106, v[166:167], off
	v_lshl_add_u64 v[166:167], v[166:167], 0, s[70:71]
	global_load_dword v107, v[166:167], off
	v_lshl_add_u64 v[166:167], v[166:167], 0, s[70:71]
	global_load_dword v108, v[166:167], off
	v_lshl_add_u64 v[166:167], v[166:167], 0, s[70:71]
	global_load_dword v109, v[166:167], off
	v_lshl_add_u64 v[166:167], v[166:167], 0, s[70:71]
	global_load_dword v110, v[166:167], off
	v_lshl_add_u64 v[166:167], v[166:167], 0, s[70:71]
	global_load_dword v111, v[166:167], off
	v_lshl_add_u64 v[166:167], v[166:167], 0, s[70:71]
	global_load_dword v112, v[166:167], off
	v_lshl_add_u64 v[166:167], v[166:167], 0, s[70:71]
	global_load_dword v113, v[166:167], off
	v_lshl_add_u64 v[166:167], v[166:167], 0, s[70:71]
	global_load_dword v114, v[166:167], off
	v_lshl_add_u64 v[166:167], v[166:167], 0, s[70:71]
	global_load_dword v115, v[166:167], off
	v_lshl_add_u64 v[166:167], v[166:167], 0, s[70:71]
	global_load_dword v116, v[166:167], off
	v_lshl_add_u64 v[166:167], v[166:167], 0, s[70:71]
	global_load_dword v117, v[166:167], off
	v_lshl_add_u64 v[166:167], v[166:167], 0, s[70:71]
	global_load_dword v118, v[166:167], off
	v_lshl_add_u64 v[166:167], v[166:167], 0, s[70:71]
	global_load_dword v119, v[166:167], off
	v_lshl_add_u64 v[166:167], v[166:167], 0, s[70:71]
	global_load_dword v120, v[166:167], off
	v_lshl_add_u64 v[166:167], v[166:167], 0, s[70:71]
	global_load_dword v121, v[166:167], off
	v_lshl_add_u64 v[166:167], v[166:167], 0, s[70:71]
	global_load_dword v122, v[166:167], off
	v_lshl_add_u64 v[166:167], v[166:167], 0, s[70:71]
	global_load_dword v123, v[166:167], off
	v_lshl_add_u64 v[166:167], v[166:167], 0, s[70:71]
	global_load_dword v124, v[166:167], off
	v_lshl_add_u64 v[166:167], v[166:167], 0, s[70:71]
	global_load_dword v125, v[166:167], off
	v_lshl_add_u64 v[166:167], v[166:167], 0, s[70:71]
	global_load_dword v126, v[166:167], off
	v_lshl_add_u64 v[166:167], v[166:167], 0, s[70:71]
	global_load_dword v127, v[166:167], off
	v_lshl_add_u64 v[166:167], v[166:167], 0, s[70:71]
	global_load_dword v128, v[166:167], off
	v_lshl_add_u64 v[166:167], v[166:167], 0, s[70:71]
	global_load_dword v129, v[166:167], off
	v_lshl_add_u64 v[166:167], v[166:167], 0, s[70:71]
	global_load_dword v130, v[166:167], off
	v_lshl_add_u64 v[166:167], v[166:167], 0, s[70:71]
	global_load_dword v131, v[166:167], off
	v_lshl_add_u64 v[166:167], v[166:167], 0, s[70:71]
	global_load_dword v132, v[166:167], off
	v_lshl_add_u64 v[166:167], v[166:167], 0, s[70:71]
	global_load_dword v133, v[166:167], off

.LBB0_1613:
	v_ashrrev_i32_e32 v8, 31, v13
	v_lshrrev_b32_e32 v8, 27, v8
	v_add_u32_e32 v8, v13, v8
	v_ashrrev_i32_e32 v8, 5, v8
	v_lshlrev_b32_e32 v9, 10, v8
	v_add_u32_e32 v10, v5, v12
	v_sub_u32_e32 v10, v10, v9
	v_cmp_lt_i32_e32 vcc, s33, v10
	v_lshlrev_b32_e32 v8, 6, v8
	v_ashrrev_i32_e32 v11, 31, v10
	v_lshl_add_u64 v[10:11], v[10:11], 2, s[2:3]
	v_or_b32_e32 v134, v8, v2
	v_ashrrev_i32_e32 v135, 31, v134
	v_lshlrev_b64 v[166:167], 12, v[134:135]
	v_lshl_add_u64 v[166:167], v[10:11], 0, v[166:167]
	s_mov_b32 s70, 0x2000
	s_mov_b32 s71, 0
	v_mov_b64_e32 v[102:103], 0
	v_mov_b64_e32 v[104:105], 0
	v_mov_b64_e32 v[106:107], 0
	v_mov_b64_e32 v[108:109], 0
	v_mov_b64_e32 v[110:111], 0
	v_mov_b64_e32 v[112:113], 0
	v_mov_b64_e32 v[114:115], 0
	v_mov_b64_e32 v[116:117], 0
	v_mov_b64_e32 v[118:119], 0
	v_mov_b64_e32 v[120:121], 0
	v_mov_b64_e32 v[122:123], 0
	v_mov_b64_e32 v[124:125], 0
	v_mov_b64_e32 v[126:127], 0
	v_mov_b64_e32 v[128:129], 0
	v_mov_b64_e32 v[130:131], 0
	v_mov_b64_e32 v[132:133], 0
	s_mov_b64 s[46:47], exec
	s_andn2_b64 exec, exec, vcc
	s_cbranch_execz .Ltr_skip_1613
	global_load_dword v102, v[166:167], off
	v_lshl_add_u64 v[166:167], v[166:167], 0, s[70:71]
	global_load_dword v103, v[166:167], off
	v_lshl_add_u64 v[166:167], v[166:167], 0, s[70:71]
	global_load_dword v104, v[166:167], off
	v_lshl_add_u64 v[166:167], v[166:167], 0, s[70:71]
	global_load_dword v105, v[166:167], off
	v_lshl_add_u64 v[166:167], v[166:167], 0, s[70:71]
	global_load_dword v106, v[166:167], off
	v_lshl_add_u64 v[166:167], v[166:167], 0, s[70:71]
	global_load_dword v107, v[166:167], off
	v_lshl_add_u64 v[166:167], v[166:167], 0, s[70:71]
	global_load_dword v108, v[166:167], off
	v_lshl_add_u64 v[166:167], v[166:167], 0, s[70:71]
	global_load_dword v109, v[166:167], off
	v_lshl_add_u64 v[166:167], v[166:167], 0, s[70:71]
	global_load_dword v110, v[166:167], off
	v_lshl_add_u64 v[166:167], v[166:167], 0, s[70:71]
	global_load_dword v111, v[166:167], off
	v_lshl_add_u64 v[166:167], v[166:167], 0, s[70:71]
	global_load_dword v112, v[166:167], off
	v_lshl_add_u64 v[166:167], v[166:167], 0, s[70:71]
	global_load_dword v113, v[166:167], off
	v_lshl_add_u64 v[166:167], v[166:167], 0, s[70:71]
	global_load_dword v114, v[166:167], off
	v_lshl_add_u64 v[166:167], v[166:167], 0, s[70:71]
	global_load_dword v115, v[166:167], off
	v_lshl_add_u64 v[166:167], v[166:167], 0, s[70:71]
	global_load_dword v116, v[166:167], off
	v_lshl_add_u64 v[166:167], v[166:167], 0, s[70:71]
	global_load_dword v117, v[166:167], off
	v_lshl_add_u64 v[166:167], v[166:167], 0, s[70:71]
	global_load_dword v118, v[166:167], off
	v_lshl_add_u64 v[166:167], v[166:167], 0, s[70:71]
	global_load_dword v119, v[166:167], off
	v_lshl_add_u64 v[166:167], v[166:167], 0, s[70:71]
	global_load_dword v120, v[166:167], off
	v_lshl_add_u64 v[166:167], v[166:167], 0, s[70:71]
	global_load_dword v121, v[166:167], off
	v_lshl_add_u64 v[166:167], v[166:167], 0, s[70:71]
	global_load_dword v122, v[166:167], off
	v_lshl_add_u64 v[166:167], v[166:167], 0, s[70:71]
	global_load_dword v123, v[166:167], off
	v_lshl_add_u64 v[166:167], v[166:167], 0, s[70:71]
	global_load_dword v124, v[166:167], off
	v_lshl_add_u64 v[166:167], v[166:167], 0, s[70:71]
	global_load_dword v125, v[166:167], off
	v_lshl_add_u64 v[166:167], v[166:167], 0, s[70:71]
	global_load_dword v126, v[166:167], off
	v_lshl_add_u64 v[166:167], v[166:167], 0, s[70:71]
	global_load_dword v127, v[166:167], off
	v_lshl_add_u64 v[166:167], v[166:167], 0, s[70:71]
	global_load_dword v128, v[166:167], off
	v_lshl_add_u64 v[166:167], v[166:167], 0, s[70:71]
	global_load_dword v129, v[166:167], off
	v_lshl_add_u64 v[166:167], v[166:167], 0, s[70:71]
	global_load_dword v130, v[166:167], off
	v_lshl_add_u64 v[166:167], v[166:167], 0, s[70:71]
	global_load_dword v131, v[166:167], off
	v_lshl_add_u64 v[166:167], v[166:167], 0, s[70:71]
	global_load_dword v132, v[166:167], off
	v_lshl_add_u64 v[166:167], v[166:167], 0, s[70:71]
	global_load_dword v133, v[166:167], off

.LBB0_1645:
	s_or_b64 exec, exec, s[20:21]
	s_mov_b64 s[20:21], 0
	s_cmp_eq_u32 s22, 0x800
	s_cselect_b32 s70, 0x100, 0
	v_add_u32_e32 v170, s70, v28
	v_cmp_le_i32_e32 vcc, s22, v170
	v_subrev_u32_e32 v174, s22, v170
	s_nop 0
	v_cndmask_b32_e32 v170, v170, v174, vcc
	v_cmp_gt_i32_e32 vcc, 0x20, v170
	s_and_saveexec_b64 s[2:3], vcc
	s_cbranch_execz .LBB0_1074
	s_add_u32 s23, s88, s20
	s_addc_u32 s26, s89, s21
	s_lshl_b64 s[20:21], s[34:35], 18
	s_add_u32 s20, s23, s20
	v_lshl_add_u64 v[6:7], s[0:1], 0, v[168:169]
	s_mov_b64 s[0:1], 0x1f00000
	s_addc_u32 s21, s26, s21
	v_lshl_add_u64 v[6:7], v[6:7], 0, s[0:1]
	s_lshl_b32 s23, s22, 5
	s_mov_b64 s[0:1], 0
	v_mov_b32_e32 v12, v170
	v_lshlrev_b32_e32 v78, 5, v170
	s_branch .LBB0_1648

.LBB0_1648:
	v_ashrrev_i32_e32 v8, 31, v12
	v_lshrrev_b32_e32 v8, 29, v8
	v_add_u32_e32 v8, v12, v8
	v_ashrrev_i32_e32 v8, 3, v8
	v_lshlrev_b32_e32 v9, 8, v8
	v_add_u32_e32 v10, v5, v78
	v_sub_u32_e32 v10, v10, v9
	s_movk_i32 s26, 0xff
	v_cmp_lt_i32_e32 vcc, s26, v10
	v_add_u32_e32 v13, v16, v17
	v_lshlrev_b32_e32 v8, 6, v8
	v_ashrrev_i32_e32 v11, 31, v10
	v_lshl_add_u64 v[10:11], v[10:11], 2, s[20:21]
	v_or_b32_e32 v134, v8, v2
	v_ashrrev_i32_e32 v135, 31, v134
	v_lshlrev_b64 v[166:167], 10, v[134:135]
	v_lshl_add_u64 v[166:167], v[10:11], 0, v[166:167]
	s_mov_b32 s70, 0x800
	s_mov_b32 s71, 0
	v_mov_b64_e32 v[102:103], 0
	v_mov_b64_e32 v[104:105], 0
	v_mov_b64_e32 v[106:107], 0
	v_mov_b64_e32 v[108:109], 0
	v_mov_b64_e32 v[110:111], 0
	v_mov_b64_e32 v[112:113], 0
	v_mov_b64_e32 v[114:115], 0
	v_mov_b64_e32 v[116:117], 0
	v_mov_b64_e32 v[118:119], 0
	v_mov_b64_e32 v[120:121], 0
	v_mov_b64_e32 v[122:123], 0
	v_mov_b64_e32 v[124:125], 0
	v_mov_b64_e32 v[126:127], 0
	v_mov_b64_e32 v[128:129], 0
	v_mov_b64_e32 v[130:131], 0
	v_mov_b64_e32 v[132:133], 0
	s_mov_b64 s[26:27], exec
	s_andn2_b64 exec, exec, vcc
	s_cbranch_execz .Ltr_skip_1648
	global_load_dword v102, v[166:167], off
	v_lshl_add_u64 v[166:167], v[166:167], 0, s[70:71]
	global_load_dword v103, v[166:167], off
	v_lshl_add_u64 v[166:167], v[166:167], 0, s[70:71]
	global_load_dword v104, v[166:167], off
	v_lshl_add_u64 v[166:167], v[166:167], 0, s[70:71]
	global_load_dword v105, v[166:167], off
	v_lshl_add_u64 v[166:167], v[166:167], 0, s[70:71]
	global_load_dword v106, v[166:167], off
	v_lshl_add_u64 v[166:167], v[166:167], 0, s[70:71]
	global_load_dword v107, v[166:167], off
	v_lshl_add_u64 v[166:167], v[166:167], 0, s[70:71]
	global_load_dword v108, v[166:167], off
	v_lshl_add_u64 v[166:167], v[166:167], 0, s[70:71]
	global_load_dword v109, v[166:167], off
	v_lshl_add_u64 v[166:167], v[166:167], 0, s[70:71]
	global_load_dword v110, v[166:167], off
	v_lshl_add_u64 v[166:167], v[166:167], 0, s[70:71]
	global_load_dword v111, v[166:167], off
	v_lshl_add_u64 v[166:167], v[166:167], 0, s[70:71]
	global_load_dword v112, v[166:167], off
	v_lshl_add_u64 v[166:167], v[166:167], 0, s[70:71]
	global_load_dword v113, v[166:167], off
	v_lshl_add_u64 v[166:167], v[166:167], 0, s[70:71]
	global_load_dword v114, v[166:167], off
	v_lshl_add_u64 v[166:167], v[166:167], 0, s[70:71]
	global_load_dword v115, v[166:167], off
	v_lshl_add_u64 v[166:167], v[166:167], 0, s[70:71]
	global_load_dword v116, v[166:167], off
	v_lshl_add_u64 v[166:167], v[166:167], 0, s[70:71]
	global_load_dword v117, v[166:167], off
	v_lshl_add_u64 v[166:167], v[166:167], 0, s[70:71]
	global_load_dword v118, v[166:167], off
	v_lshl_add_u64 v[166:167], v[166:167], 0, s[70:71]
	global_load_dword v119, v[166:167], off
	v_lshl_add_u64 v[166:167], v[166:167], 0, s[70:71]
	global_load_dword v120, v[166:167], off
	v_lshl_add_u64 v[166:167], v[166:167], 0, s[70:71]
	global_load_dword v121, v[166:167], off
	v_lshl_add_u64 v[166:167], v[166:167], 0, s[70:71]
	global_load_dword v122, v[166:167], off
	v_lshl_add_u64 v[166:167], v[166:167], 0, s[70:71]
	global_load_dword v123, v[166:167], off
	v_lshl_add_u64 v[166:167], v[166:167], 0, s[70:71]
	global_load_dword v124, v[166:167], off
	v_lshl_add_u64 v[166:167], v[166:167], 0, s[70:71]
	global_load_dword v125, v[166:167], off
	v_lshl_add_u64 v[166:167], v[166:167], 0, s[70:71]
	global_load_dword v126, v[166:167], off
	v_lshl_add_u64 v[166:167], v[166:167], 0, s[70:71]
	global_load_dword v127, v[166:167], off
	v_lshl_add_u64 v[166:167], v[166:167], 0, s[70:71]
	global_load_dword v128, v[166:167], off
	v_lshl_add_u64 v[166:167], v[166:167], 0, s[70:71]
	global_load_dword v129, v[166:167], off
	v_lshl_add_u64 v[166:167], v[166:167], 0, s[70:71]
	global_load_dword v130, v[166:167], off
	v_lshl_add_u64 v[166:167], v[166:167], 0, s[70:71]
	global_load_dword v131, v[166:167], off
	v_lshl_add_u64 v[166:167], v[166:167], 0, s[70:71]
	global_load_dword v132, v[166:167], off
	v_lshl_add_u64 v[166:167], v[166:167], 0, s[70:71]
	global_load_dword v133, v[166:167], off
